# hy_conv long-sequence tap loop: tap range split across the two wave pairs so each filter fragment feeds two MFMAs (25% less LDS traffic), partial sums swapped through LDS
# speedup vs baseline: 1.1160x; 1.0033x over previous
.LBB0_705:
	s_cmp_eq_u32 s73, 64
	s_cbranch_scc1 .Lconv_lat2
	v_mov_b32_e32 v221, 0x11040
	v_cmp_gt_u32_e32 vcc, s73, v32
	v_lshl_add_u32 v220, v33, 1, v121
	s_nop 1
	v_cndmask_b32_e32 v220, v221, v220, vcc
	ds_read2_b32 v[36:37], v34 offset1:1
	ds_read2_b32 v[38:39], v34 offset0:2 offset1:3
	ds_read_b128 v[40:43], v220
	ds_read_b128 v[44:47], v220 offset:32
	ds_read2_b32 v[200:201], v34 offset0:8 offset1:9
	ds_read2_b32 v[202:203], v34 offset0:10 offset1:11
.Lconv_loop:
	v_add_u32_e32 v35, 1, v35
	v_add_u32_e32 v32, -1, v32
	v_cmp_gt_u32_e32 vcc, s73, v32
	v_subrev_u32_e32 v33, 40, v33
	v_subrev_u32_e32 v34, 64, v34
	v_lshl_add_u32 v220, v33, 1, v121
	v_cndmask_b32_e32 v220, v221, v220, vcc
	ds_read2_b32 v[204:205], v34 offset1:1
	ds_read2_b32 v[206:207], v34 offset0:2 offset1:3
	ds_read_b128 v[208:211], v220
	ds_read_b128 v[212:215], v220 offset:32
	ds_read2_b32 v[216:217], v34 offset0:8 offset1:9
	ds_read2_b32 v[218:219], v34 offset0:10 offset1:11
	s_waitcnt lgkmcnt(6)
	v_mfma_f32_32x32x16_bf16 v[0:15], v[36:39], v[40:43], v[0:15]
	v_mfma_f32_32x32x16_bf16 v[0:15], v[200:203], v[44:47], v[0:15]
	v_cmp_ge_i32_e32 vcc, v35, v61
	s_or_b64 s[10:11], vcc, s[10:11]
	s_andn2_b64 exec, exec, s[10:11]
	s_cbranch_execz .Lconv_exit
	v_add_u32_e32 v35, 1, v35
	v_add_u32_e32 v32, -1, v32
	v_cmp_gt_u32_e32 vcc, s73, v32
	v_subrev_u32_e32 v33, 40, v33
	v_subrev_u32_e32 v34, 64, v34
	v_lshl_add_u32 v220, v33, 1, v121
	v_cndmask_b32_e32 v220, v221, v220, vcc
	ds_read2_b32 v[36:37], v34 offset1:1
	ds_read2_b32 v[38:39], v34 offset0:2 offset1:3
	ds_read_b128 v[40:43], v220
	ds_read_b128 v[44:47], v220 offset:32
	ds_read2_b32 v[200:201], v34 offset0:8 offset1:9
	ds_read2_b32 v[202:203], v34 offset0:10 offset1:11
	s_waitcnt lgkmcnt(6)
	v_mfma_f32_32x32x16_bf16 v[0:15], v[204:207], v[208:211], v[0:15]
	v_mfma_f32_32x32x16_bf16 v[0:15], v[216:219], v[212:215], v[0:15]
	v_cmp_ge_i32_e32 vcc, v35, v61
	s_or_b64 s[10:11], vcc, s[10:11]
	s_andn2_b64 exec, exec, s[10:11]
	s_cbranch_execnz .Lconv_loop
	s_branch .Lconv_exit
.Lconv_lat2:
	v_lshrrev_b32_e32 v212, 7, v176
	s_nop 0
	v_readfirstlane_b32 s101, v212
	v_sub_u32_e32 v212, v61, v35
	s_nop 0
	v_readfirstlane_b32 s100, v212
	s_cmp_eq_u32 s101, 0
	s_cbranch_scc1 .Lcl2_h0
	s_sub_i32 s100, s100, 48
	v_add_u32_e32 v32, 0xffffffd0, v32
	v_add_u32_e32 v33, 0xfffff880, v33
	v_add_u32_e32 v34, 0xfffff400, v34
	v_add_u32_e32 v213, 0xffffec00, v121
	s_branch .Lcl2_go
.Lcl2_h0:
	s_mov_b32 s100, 48
	v_add_u32_e32 v213, 0x1400, v121
.Lcl2_go:
	s_max_i32 s100, s100, 1
	s_min_i32 s100, s100, 0x100
	v_mov_b32_e32 v221, 0x11040
	v_mov_b32_e32 v236, 0
	v_mov_b32_e32 v237, 0
	v_mov_b32_e32 v238, 0
	v_mov_b32_e32 v239, 0
	v_mov_b32_e32 v240, 0
	v_mov_b32_e32 v241, 0
	v_mov_b32_e32 v242, 0
	v_mov_b32_e32 v243, 0
	v_mov_b32_e32 v244, 0
	v_mov_b32_e32 v245, 0
	v_mov_b32_e32 v246, 0
	v_mov_b32_e32 v247, 0
	v_mov_b32_e32 v248, 0
	v_mov_b32_e32 v249, 0
	v_mov_b32_e32 v250, 0
	v_mov_b32_e32 v251, 0
.Lcl2_loop:
	v_cmp_gt_u32_e32 vcc, s73, v32
	v_lshl_add_u32 v220, v33, 1, v121
	v_lshl_add_u32 v212, v33, 1, v213
	ds_read2_b32 v[36:37], v34 offset1:1
	ds_read2_b32 v[38:39], v34 offset0:2 offset1:3
	ds_read2_b32 v[200:201], v34 offset0:8 offset1:9
	ds_read2_b32 v[202:203], v34 offset0:10 offset1:11
	v_cndmask_b32_e32 v220, v221, v220, vcc
	v_cndmask_b32_e32 v212, v221, v212, vcc
	ds_read_b128 v[40:43], v220
	ds_read_b128 v[44:47], v220 offset:32
	ds_read_b128 v[204:207], v212
	ds_read_b128 v[208:211], v212 offset:32
	v_add_u32_e32 v32, -1, v32
	v_subrev_u32_e32 v33, 40, v33
	v_subrev_u32_e32 v34, 64, v34
	s_waitcnt lgkmcnt(0)
	v_mfma_f32_32x32x16_bf16 v[0:15], v[36:39], v[40:43], v[0:15]
	v_mfma_f32_32x32x16_bf16 v[236:251], v[36:39], v[204:207], v[236:251]
	v_mfma_f32_32x32x16_bf16 v[0:15], v[200:203], v[44:47], v[0:15]
	v_mfma_f32_32x32x16_bf16 v[236:251], v[200:203], v[208:211], v[236:251]
	s_add_i32 s100, s100, -1
	s_cmp_lg_u32 s100, 0
	s_cbranch_scc1 .Lcl2_loop
	v_lshrrev_b32_e32 v214, 6, v176
	v_and_b32_e32 v216, 63, v176
	v_lshlrev_b32_e32 v216, 4, v216
	v_lshl_add_u32 v215, v214, 12, v216
	v_xor_b32_e32 v214, 2, v214
	v_lshl_add_u32 v214, v214, 12, v216
	s_nop 15
	s_waitcnt lgkmcnt(0)
	s_barrier
	ds_write_b128 v214, v[236:239] offset:53248
	ds_write_b128 v214, v[240:243] offset:54272
	ds_write_b128 v214, v[244:247] offset:55296
	ds_write_b128 v214, v[248:251] offset:56320
	s_waitcnt lgkmcnt(0)
	s_barrier
	ds_read_b128 v[200:203], v215 offset:53248
	ds_read_b128 v[204:207], v215 offset:54272
	ds_read_b128 v[208:211], v215 offset:55296
	ds_read_b128 v[216:219], v215 offset:56320
	s_waitcnt lgkmcnt(0)
	v_add_f32_e32 v0, v0, v200
	v_add_f32_e32 v1, v1, v201
	v_add_f32_e32 v2, v2, v202
	v_add_f32_e32 v3, v3, v203
	v_add_f32_e32 v4, v4, v204
	v_add_f32_e32 v5, v5, v205
	v_add_f32_e32 v6, v6, v206
	v_add_f32_e32 v7, v7, v207
	v_add_f32_e32 v8, v8, v208
	v_add_f32_e32 v9, v9, v209
	v_add_f32_e32 v10, v10, v210
	v_add_f32_e32 v11, v11, v211
	v_add_f32_e32 v12, v12, v216
	v_add_f32_e32 v13, v13, v217
	v_add_f32_e32 v14, v14, v218
	v_add_f32_e32 v15, v15, v219
	s_branch .Lconv_exit
